# branch-merge GEMM: waves 4-7 at static priority 1 to stagger the two waves of each SIMD
# speedup vs baseline: 1.0127x; 1.0050x over previous
.LBB0_959:
	s_barrier
	s_andn2_b64 vcc, exec, s[8:9]
	s_cbranch_vccnz .LBB0_972
	v_bfe_u32 v3, v0, 4, 2
	v_lshrrev_b32_e32 v2, 4, v0
	v_and_b32_e32 v4, 1, v1
	v_and_b32_e32 v5, 15, v0
	v_ashrrev_i32_e32 v6, 7, v0
	v_and_b32_e32 v0, 7, v0
	v_lshlrev_b32_e32 v146, 10, v1
	v_lshlrev_b32_e32 v1, 3, v3
	v_lshl_or_b32 v155, v4, 6, v1
	v_bitop3_b32 v1, v2, v0, 3 bitop3:0x6c
	v_bitop3_b32 v0, v3, v0, 4 bitop3:0x36
	s_mul_i32 s18, s18, 24
	s_add_u32 s8, s6, 0x1abf0000
	v_lshlrev_b32_e32 v1, 4, v1
	v_lshlrev_b32_e32 v2, 13, v6
	v_lshlrev_b32_e32 v4, 13, v4
	v_lshlrev_b32_e32 v0, 4, v0
	v_mov_b32_e32 v76, 0
	s_addc_u32 s9, s7, 0
	v_lshl_or_b32 v154, v6, 6, v5
	s_max_u32 s19, s18, 1
	v_lshl_add_u32 v156, v5, 7, 0
	v_or_b32_e32 v157, v4, v0
	v_or_b32_e32 v158, v2, v1
	v_or_b32_e32 v159, v4, v1
	v_or_b32_e32 v160, v2, v0
	s_mov_b32 s20, 0
	s_mov_b32 s21, 2
	s_movk_i32 s22, 0x80
	s_mov_b32 s23, 0
	v_mov_b32_e32 v77, v76
	v_mov_b32_e32 v78, v76
	v_mov_b32_e32 v79, v76
	v_mov_b32_e32 v82, v76
	v_mov_b32_e32 v83, v76
	v_mov_b32_e32 v80, v76
	v_mov_b32_e32 v81, v76
	v_mov_b32_e32 v86, v76
	v_mov_b32_e32 v87, v76
	v_mov_b32_e32 v84, v76
	v_mov_b32_e32 v85, v76
	v_mov_b32_e32 v90, v76
	v_mov_b32_e32 v91, v76
	v_mov_b32_e32 v88, v76
	v_mov_b32_e32 v89, v76
	v_mov_b32_e32 v94, v76
	v_mov_b32_e32 v95, v76
	v_mov_b32_e32 v92, v76
	v_mov_b32_e32 v93, v76
	v_mov_b32_e32 v98, v76
	v_mov_b32_e32 v99, v76
	v_mov_b32_e32 v96, v76
	v_mov_b32_e32 v97, v76
	v_mov_b32_e32 v102, v76
	v_mov_b32_e32 v103, v76
	v_mov_b32_e32 v100, v76
	v_mov_b32_e32 v101, v76
	v_mov_b32_e32 v106, v76
	v_mov_b32_e32 v107, v76
	v_mov_b32_e32 v104, v76
	v_mov_b32_e32 v105, v76
	v_mov_b32_e32 v110, v76
	v_mov_b32_e32 v111, v76
	v_mov_b32_e32 v108, v76
	v_mov_b32_e32 v109, v76
	v_mov_b32_e32 v114, v76
	v_mov_b32_e32 v115, v76
	v_mov_b32_e32 v112, v76
	v_mov_b32_e32 v113, v76
	v_mov_b32_e32 v118, v76
	v_mov_b32_e32 v119, v76
	v_mov_b32_e32 v116, v76
	v_mov_b32_e32 v117, v76
	v_mov_b32_e32 v122, v76
	v_mov_b32_e32 v123, v76
	v_mov_b32_e32 v120, v76
	v_mov_b32_e32 v121, v76
	v_mov_b32_e32 v126, v76
	v_mov_b32_e32 v127, v76
	v_mov_b32_e32 v124, v76
	v_mov_b32_e32 v125, v76
	v_mov_b32_e32 v130, v76
	v_mov_b32_e32 v131, v76
	v_mov_b32_e32 v128, v76
	v_mov_b32_e32 v129, v76
	v_mov_b32_e32 v134, v76
	v_mov_b32_e32 v135, v76
	v_mov_b32_e32 v132, v76
	v_mov_b32_e32 v133, v76
	v_mov_b32_e32 v138, v76
	v_mov_b32_e32 v139, v76
	v_mov_b32_e32 v136, v76
	v_mov_b32_e32 v137, v76
	v_mov_b32_e32 v0, v76
	v_mov_b32_e32 v1, v76
	v_mov_b32_e32 v2, v76
	v_mov_b32_e32 v3, v76
	v_mov_b32_e32 v4, v76
	v_mov_b32_e32 v5, v76
	v_mov_b32_e32 v6, v76
	v_mov_b32_e32 v7, v76
	s_waitcnt vmcnt(0)
	v_mov_b32_e32 v8, v76
	v_mov_b32_e32 v9, v76
	v_mov_b32_e32 v10, v76
	v_mov_b32_e32 v11, v76
	v_mov_b32_e32 v12, v76
	v_mov_b32_e32 v13, v76
	v_mov_b32_e32 v14, v76
	v_mov_b32_e32 v15, v76
	v_mov_b32_e32 v16, v76
	v_mov_b32_e32 v17, v76
	v_mov_b32_e32 v18, v76
	v_mov_b32_e32 v19, v76
	v_mov_b32_e32 v20, v76
	v_mov_b32_e32 v21, v76
	v_mov_b32_e32 v22, v76
	v_mov_b32_e32 v23, v76
	v_mov_b32_e32 v24, v76
	v_mov_b32_e32 v25, v76
	v_mov_b32_e32 v26, v76
	v_mov_b32_e32 v27, v76
	v_mov_b32_e32 v28, v76
	v_mov_b32_e32 v29, v76
	v_mov_b32_e32 v30, v76
	v_mov_b32_e32 v31, v76
	v_mov_b32_e32 v32, v76
	v_mov_b32_e32 v33, v76
	v_mov_b32_e32 v34, v76
	v_mov_b32_e32 v35, v76
	v_mov_b32_e32 v36, v76
	v_mov_b32_e32 v37, v76
	v_mov_b32_e32 v38, v76
	v_mov_b32_e32 v39, v76
	v_mov_b32_e32 v40, v76
	v_mov_b32_e32 v41, v76
	v_mov_b32_e32 v42, v76
	v_mov_b32_e32 v43, v76
	v_mov_b32_e32 v44, v76
	v_mov_b32_e32 v45, v76
	v_mov_b32_e32 v46, v76
	v_mov_b32_e32 v47, v76
	v_mov_b32_e32 v48, v76
	v_mov_b32_e32 v49, v76
	v_mov_b32_e32 v50, v76
	v_mov_b32_e32 v51, v76
	v_mov_b32_e32 v52, v76
	v_mov_b32_e32 v53, v76
	v_mov_b32_e32 v54, v76
	v_mov_b32_e32 v55, v76
	v_mov_b32_e32 v56, v76
	v_mov_b32_e32 v57, v76
	v_mov_b32_e32 v58, v76
	v_mov_b32_e32 v59, v76
	v_mov_b32_e32 v60, v76
	v_mov_b32_e32 v61, v76
	v_mov_b32_e32 v62, v76
	v_mov_b32_e32 v63, v76
	s_load_dword s43, s[38:39], 0x10
	s_mov_b32 s5, 0
	s_waitcnt lgkmcnt(0)
	v_readfirstlane_b32 s0, v226
	s_lshr_b32 s0, s0, 8
	s_cmp_eq_u32 s0, 1
	s_cbranch_scc0 .Lp6_noprio
	s_setprio 1
.Lp6_noprio:
	v_subrev_u32_e32 v141, s5, v158
	v_add_u32_e32 v140, s20, v156
	v_subrev_u32_e32 v142, s5, v159
	v_add_u32_e32 v141, v140, v141
	ds_read_b128 v[162:165], v141
	ds_read_b128 v[166:169], v141 offset:2048
	ds_read_b128 v[170:173], v141 offset:4096
	ds_read_b128 v[174:177], v141 offset:6144
	v_add_u32_e32 v141, v140, v142
	ds_read_b128 v[178:181], v141 offset:32768
	ds_read_b128 v[182:185], v141 offset:34816
	ds_read_b128 v[186:189], v141 offset:36864
	ds_read_b128 v[190:193], v141 offset:38912
	s_branch .Lp6_top

.LBB0_972:
	s_setprio 0
	s_mov_b64 s[8:9], s[70:71]
	s_waitcnt vmcnt(0) lgkmcnt(0)
	s_barrier
	s_getreg_b32 s4, hwreg(HW_REG_XCC_ID, 0, 4)
	s_waitcnt vmcnt(0)
	v_mov_b32_e32 v0, v226
	s_barrier
	s_nop 0
	v_cmp_eq_u32_e32 vcc, 0, v0
	s_and_saveexec_b64 s[0:1], vcc
	s_xor_b64 s[6:7], exec, s[0:1]
	s_cbranch_execz .LBB0_1025
	v_readlane_b32 s0, v254, 60
	s_load_dwordx2 s[8:9], s[8:9], 0xc0
	s_waitcnt vmcnt(0) expcnt(0) lgkmcnt(0)
	v_mov_b32_e32 v0, s0
	ds_read_b32 v2, v0
	v_readlane_b32 s0, v254, 61
	s_and_b32 s4, s4, 15
	s_waitcnt lgkmcnt(0)
	v_cmp_ne_u32_e32 vcc, 0, v2
	v_mov_b32_e32 v0, s0
	ds_read_b32 v0, v0
	s_cbranch_vccnz .LBB0_988
	s_add_u32 s10, s8, 0x1ebfd300
	s_addc_u32 s11, s9, 0
	s_add_u32 s12, s8, 0x1ebfd500
	s_addc_u32 s13, s9, 0
	s_add_u32 s14, s8, 0x1ebfd600
	s_addc_u32 s15, s9, 0
	s_add_u32 s16, s8, 0x1ebfd700
	s_addc_u32 s17, s9, 0
	s_add_u32 s18, s8, 0x1ebfd800
	s_addc_u32 s19, s9, 0
	s_add_u32 s20, s8, 0x1ebfd900
	s_addc_u32 s21, s9, 0
	s_add_u32 s22, s8, 0x1ebfda00
	s_addc_u32 s23, s9, 0
	s_add_u32 s24, s8, 0x1ebfdb00
	s_addc_u32 s25, s9, 0
	s_add_u32 s26, s8, 0x1ebfdc00
	s_addc_u32 s27, s9, 0
	s_add_u32 s28, s8, 0x1ebfdd00
	s_addc_u32 s29, s9, 0
	s_add_u32 s30, s8, 0x1ebfde00
	s_addc_u32 s31, s9, 0
	s_add_u32 s34, s8, 0x1ebfdf00
	s_addc_u32 s35, s9, 0
	s_add_u32 s36, s8, 0x1ebfe000
	s_addc_u32 s37, s9, 0
	s_add_u32 s44, s8, 0x1ebfe100
	s_addc_u32 s45, s9, 0
	s_add_u32 s58, s8, 0x1ebfe200
	s_addc_u32 s59, s9, 0
	s_add_u32 s96, s8, 0x1ebfe300
	s_addc_u32 s97, s9, 0
	s_add_u32 s56, s8, 0x1ebfe400
	s_addc_u32 s57, s9, 0
	s_mov_b32 s5, 1
	s_branch .LBB0_976
